# hot loop heads padded to the baseline byte phase (s_nop pads executed once per phase), on top of v11
# baseline (speedup 1.0000x reference)
; template <bool PR>
; __device__ __forceinline__ void attn_unit(const Args& a, const bf16_t* QB, bf16_t* AO, const bf16_t* KBp, const bf16_t* VTp, int qt, int h, int lane) {
;     const int r32 = lane & 31, hi = lane >> 5;
;     const float *Kd, *Vd, *Kc, *Vc; int nprev; size_t qrow0;
;     if (qt < 1024) { const int b = qt >> 7, tq = qt & 127; qrow0 = (size_t)qt * 32;
;         Kc = a.out + OFF_KP + (size_t)b * 4096 * 512 + h * 64; Vc = a.out + OFF_VP + (size_t)b * 4096 * 512 + h * 64;
;         Kd = Kc + (size_t)tq * 32 * 512; Vd = Vc + (size_t)tq * 32 * 512; nprev = tq; }
;     else { const int bs = qt - 1024; qrow0 = (size_t)MP + (size_t)bs * 32;
;         Kd = a.out + OFF_KS + (size_t)bs * 32 * 512 + h * 64; Vd = a.out + OFF_VS + (size_t)bs * 32 * 512 + h * 64;
;         Kc = a.in[I_CK] + (size_t)bs * 4096 * 512 + h * 64; Vc = a.in[I_CV] + (size_t)bs * 4096 * 512 + h * 64; nprev = 128; }
;     bf16x8 qf[4];
;     { const bf16_t* Qp = QB + (qrow0 + r32) * 512 + h * 64 + hi * 8;
; #pragma unroll
;       for (int kk = 0; kk < 4; ++kk) qf[kk] = __builtin_nontemporal_load((const bf16x8*)(Qp + kk * 16)); }
;     f32x16 o0, o1;
; #pragma unroll
;     for (int r = 0; r < 16; ++r) { o0[r] = 0.f; o1[r] = 0.f; }
;     float Cm = 1.f; int Ce = 0;
;     constexpr int DP = PR ? 3 : 1;
;     f32x4 kr[8]; float vr[32];
;     bf16x8 krb[DP][4]; u32x2 vrb[DP][8];
;     const bf16_t* Kbb = KBp + (size_t)(((qt >> 7) * 8 + h) * 128) * 2048 + r32 * 16 + hi * 8;
;     const bf16_t* Vtb = VTp + ((size_t)(((qt >> 7) * 8 + h) * 1024 + hi) * 64 + r32) * 4;
;     ...
;         for (int r = 0; r < 16; ++r) { const float z2 = s[r]; const float e = __builtin_amdgcn_exp2f(-fabsf(z2)); const float rc = __builtin_amdgcn_rcpf(1.f + e); const float t = e * rc;
;             const bool pos = z2 >= 0.f; const bool valid = (it != 0) || (crow(r, hi) < r32);
;             sg[r] = valid ? (pos ? rc : t) : 0.f; om[r] = valid ? (pos ? t : rc) : 1.f; }
;         const float G0 = (om[0] * om[1]) * (om[2] * om[3]), G1 = (om[4] * om[5]) * (om[6] * om[7]), G2 = (om[8] * om[9]) * (om[10] * om[11]), G3 = (om[12] * om[13]) * (om[14] * om[15]);
;         const float P0 = __shfl_xor(G0, 32), P1 = __shfl_xor(G1, 32), P2 = __shfl_xor(G2, 32), P3 = __shfl_xor(G3, 32);
;         const float t3 = G3 * P3, t2 = G2 * P2, t1 = G1 * P1, t0 = G0 * P0;
;         const float Cs = ldexpf(Cm, Ce);
;         float base[4];
.LBB0_593:
	s_nop 0
	s_nop 0
	s_nop 0
	s_nop 0
	s_nop 0
	v_readlane_b32 s0, v241, 23
	s_cmpk_gt_u32 s0, 0x20ff
	v_cmp_eq_u32_e64 s[54:55], 0, v180
	v_readlane_b32 s56, v241, 28
	v_readlane_b32 s1, v241, 24
	v_readlane_b32 s57, v241, 29
	v_writelane_b32 v241, s94, 43
	s_cbranch_scc1 .LBB0_645
	v_and_b32_e32 v182, 31, v181
	v_lshrrev_b32_e32 v5, 5, v180
	v_mov_b32_e32 v185, 0
	v_lshlrev_b32_e32 v184, 5, v182
	v_lshl_add_u64 v[0:1], s[16:17], 0, v[184:185]
	v_lshlrev_b32_e32 v2, 4, v5
	v_mov_b32_e32 v3, v185
	v_lshl_add_u64 v[188:189], v[0:1], 0, v[2:3]
	v_lshlrev_b32_e32 v0, 2, v5
	v_or_b32_e32 v1, 1, v0
	v_cmp_lt_u32_e64 s[8:9], v1, v182
	v_or_b32_e32 v1, 2, v0
	v_cmp_lt_u32_e64 s[10:11], v1, v182
	v_or_b32_e32 v1, 3, v0
	v_cmp_lt_u32_e64 s[12:13], v1, v182
	v_or_b32_e32 v1, 8, v0
	v_cmp_lt_u32_e64 s[14:15], v1, v182
	v_or_b32_e32 v1, 9, v0
	s_add_u32 s0, s90, 0x383800
	v_cmp_lt_u32_e64 s[16:17], v1, v182
	v_or_b32_e32 v1, 10, v0
	s_addc_u32 s1, s91, 0
	v_cmp_lt_u32_e64 s[18:19], v1, v182
	v_or_b32_e32 v1, 11, v0
	v_writelane_b32 v241, s70, 44
	s_add_u32 s57, s90, 0x1dd00000
	v_cmp_lt_u32_e64 s[20:21], v1, v182
	v_or_b32_e32 v1, 16, v0
	v_writelane_b32 v241, s0, 45
	s_addc_u32 s60, s91, 0
	v_cmp_lt_u32_e64 s[22:23], v1, v182
	v_or_b32_e32 v1, 17, v0
	v_writelane_b32 v241, s1, 46
	v_cmp_lt_u32_e64 s[24:25], v1, v182
	v_or_b32_e32 v1, 18, v0
	s_add_u32 s0, s88, 0x10688000
	v_cmp_lt_u32_e64 s[26:27], v1, v182
	v_or_b32_e32 v1, 19, v0
	v_writelane_b32 v241, s0, 47
	s_addc_u32 s0, s89, 0
	v_cmp_lt_u32_e64 s[28:29], v1, v182
	v_or_b32_e32 v1, 24, v0
	v_writelane_b32 v241, s0, 48
	s_add_u32 s0, s88, 0x10488000
	v_cmp_lt_u32_e64 s[30:31], v1, v182
	v_or_b32_e32 v1, 25, v0
	v_writelane_b32 v241, s0, 49
	s_addc_u32 s0, s89, 0
	v_cmp_lt_u32_e64 s[34:35], v1, v182
	v_or_b32_e32 v1, 26, v0
	v_writelane_b32 v241, s0, 50
	v_cmp_lt_u32_e64 s[36:37], v1, v182
	v_and_b32_e32 v1, 32, v181
	v_readlane_b32 s0, v241, 23
	v_cmp_lt_u32_e64 s[6:7], v0, v182
	v_or_b32_e32 v0, 27, v0
	v_lshrrev_b32_e32 v1, 1, v1
	v_readlane_b32 s1, v241, 24
	v_writelane_b32 v241, s54, 51
	v_lshlrev_b32_e32 v186, 3, v5
	v_cmp_lt_u32_e64 s[38:39], v0, v182
	v_lshlrev_b32_e32 v0, 12, v5
	v_lshlrev_b32_e32 v2, 9, v182
	v_lshlrev_b32_e32 v4, 11, v5
	v_or_b32_e32 v184, v184, v1
	s_movk_i32 s2, 0xd000
	v_writelane_b32 v241, s55, 52
	s_mov_b32 s93, 0
	v_mov_b32_e32 v177, v185
	v_cmp_gt_u32_e64 s[4:5], 32, v180
	v_lshl_or_b32 v183, v5, 6, v182
	v_lshl_add_u64 v[190:191], s[90:91], 0, v[184:185]
	s_movk_i32 s64, 0xff6a
	s_mov_b32 s3, -1
	s_movk_i32 s70, 0x1000
	s_movk_i32 s71, 0x4000
	s_movk_i32 s66, 0x5000
	s_mov_b32 s65, 0x8000
	s_mov_b32 s67, 0x9000
	s_mov_b32 s62, 0xc000
	v_lshlrev_b32_e32 v192, 2, v2
	v_lshlrev_b32_e32 v194, 2, v4
	v_lshlrev_b32_e32 v196, 1, v0
	v_lshlrev_b32_e32 v184, 1, v186
	v_mbcnt_hi_u32_b32 v187, -1, v179
	s_mov_b32 s63, s0
	v_writelane_b32 v241, s57, 53
	v_writelane_b32 v241, s60, 54
	s_branch .LBB0_597

;     __device__ __forceinline__ bool next(int i, Unit& u) const { u.kb = 0; u.nk = 0; return static_tile(i, nM, nN, G, c, u.pm, u.pn); }
; #define PG8_STAGE(bufoff, gbase, voff) do { _Pragma("unroll") for (int _i = 0; _i < 2; ++_i) \
;         __builtin_amdgcn_global_load_lds((const unsigned*)((const char*)(gbase) + (voff)[_i]), (PG8_LAS unsigned*)(lds + (bufoff) + ldsw + _i * 8192), 16, 0, 0); } while (0)
; #define PG8_WAIT_V(n) asm volatile("s_waitcnt vmcnt(" #n ")" ::: "memory")
; #define PG8_BAR __builtin_amdgcn_s_barrier()
; __device__ __forceinline__ bool static_tile(int i, int nM, int nN, int G, int c, int& pm, int& pn) {
;     const int nwg = nM * nN; const long Lx = (long)i * G + c; if (Lx >= nwg) return false;
;     int wgid = (int)Lx; { const int q = nwg / NXCD, r = nwg % NXCD, xcd = wgid % NXCD, off = wgid / NXCD; wgid = (xcd < r ? xcd * (q + 1) : r * (q + 1) + (xcd - r) * q) + off; }
;     const int nig = WGM * nN, gid = wgid / nig, fm = gid * WGM, gsz = (nM - fm) < WGM ? (nM - fm) : WGM;
;     pm = fm + ((wgid % nig) % gsz); pn = (wgid % nig) / gsz; return true;
; template <class Epi, class Sched>
; __device__ __forceinline__ void gemm_phase(PG8_LAS unsigned char* lds, const Gemm g, const Sched& S, const Epi& E) {
;     ...
;     for (int i = 0; i < 2; ++i) { int R, C; stage_rc(tid * 16 + i * 8192, R, C); const int Rb = (R & ~31) + perm32(R & 31);
;         voffA[i] = (unsigned)(R * g.lda + C) * 2u; voffB[i] = (unsigned)(Rb * K + C) * 2u; }
;     const size_t kstep = (size_t)(BK * 2);
;     const size_t hstepA = (size_t)HALF * g.lda * 2, hstepB = (size_t)HALF * K * 2;
;     const unsigned ldsw = (unsigned)wid * 1024u;
;     const int aoff = lds_byte(wr * 64 + fr, fq * 8), boff = lds_byte(wc * 32 + fr, fq * 8);
;     ...
;     Unit cur, nxt; int ui = 0;
;     if (!S.next(0, cur)) return;
;     f32x4 acc[2][2][4][2];
;     E.init(acc, cur, wr, wc, fr, fq);
;     bf16x8 At[4][2], B0[2][2], B1[2][2];
;     const char* cA = PG8_TA(cur); const char* cB = PG8_TB(cur);
;     PG8_STAGE(PG8_SB(0, 0), cB, voffB); PG8_STAGE(PG8_SB(0, 1), cB + hstepB, voffB); PG8_STAGE(PG8_SA(0, 0), cA, voffA); PG8_STAGE(PG8_SA(0, 1), cA + hstepA, voffA);
;     if (wr == 1) PG8_BAR;
;     PG8_WAIT_V(2); PG8_BAR;
;     PG8_STAGE(PG8_SB(1, 0), cB + kstep, voffB); PG8_STAGE(PG8_SA(1, 0), cA + kstep, voffA); PG8_STAGE(PG8_SB(1, 1), cB + hstepB + kstep, voffB);
.LBB0_935:
	s_or_b64 exec, exec, s[0:1]
	s_waitcnt vmcnt(3)
	v_mov_b32_e32 v13, v181
	s_cmpk_lt_i32 s66, 0xb58
	s_waitcnt lgkmcnt(0)
	s_barrier
	s_nop 0
	s_nop 0
	s_nop 0
	s_nop 0
	s_movk_i32 s0, 0x400
	v_readfirstlane_b32 s2, v13
	s_cselect_b64 s[24:25], -1, 0
	s_cmpk_gt_i32 s66, 0xb57
	s_cbranch_scc1 .LBB0_954
	s_waitcnt vmcnt(1)
	v_lshlrev_b32_e32 v0, 4, v13
	v_add_u32_e32 v1, 0x2000, v0
	v_ashrrev_i32_e32 v2, 31, v1
	v_lshrrev_b32_e32 v2, 22, v2
	v_add_u32_e32 v2, v1, v2
	v_ashrrev_i32_e32 v12, 10, v2
	v_mul_i32_i24_e32 v2, 0x400, v12
	v_sub_u32_e32 v1, v1, v2
	v_lshrrev_b32_e32 v2, 4, v1
	v_bitop3_b32 v1, v2, v1, 32 bitop3:0x6c
	v_ashrrev_i32_e32 v2, 31, v1
	v_lshrrev_b32_e32 v2, 26, v2
	v_add_u32_e32 v2, v1, v2
	v_lshlrev_b32_e32 v3, 3, v12
	v_ashrrev_i32_e32 v14, 6, v2
	v_and_b32_e32 v3, -16, v3
	v_add_u32_e32 v3, v14, v3
	s_waitcnt vmcnt(0)
	v_and_b32_e32 v4, 3, v14
	s_mov_b32 s4, 0x7fffffe0
	v_lshrrev_b32_e32 v5, 2, v3
	v_lshlrev_b32_e32 v6, 1, v3
	v_and_b32_e32 v2, 0xc0, v2
	v_and_or_b32 v4, v3, s4, v4
	v_and_b32_e32 v5, 4, v5
	v_and_b32_e32 v6, 24, v6
	v_sub_u32_e32 v1, v1, v2
	v_mov_b32_e32 v2, 1
	v_or3_b32 v4, v4, v5, v6
	v_lshlrev_b32_e32 v5, 5, v12
	v_ashrrev_i16_sdwa v1, v2, sext(v1) dst_sel:DWORD dst_unused:UNUSED_PAD src0_sel:DWORD src1_sel:BYTE_0
	v_and_b32_e32 v5, 32, v5
	v_bfe_i32 v15, v1, 0, 16
	v_mul_lo_u32 v4, v4, s0
	v_add_u32_e32 v1, v5, v15
	v_lshlrev_b32_e32 v3, 11, v3
	v_add_lshl_u32 v128, v4, v1, 1
	v_lshl_add_u32 v130, v1, 1, v3
	v_bfe_i32 v1, v13, 27, 1
	v_lshrrev_b32_e32 v1, 22, v1
	v_add_u32_e32 v1, v0, v1
	v_and_b32_e32 v1, 0xfffffc00, v1
	v_sub_u32_e32 v0, v0, v1
	v_lshrrev_b32_e32 v1, 4, v0
	v_ashrrev_i32_e32 v3, 31, v13
	v_bitop3_b32 v0, v1, v0, 32 bitop3:0x6c
	v_lshrrev_b32_e32 v3, 26, v3
	v_ashrrev_i32_e32 v1, 31, v0
	v_add_u32_e32 v3, v13, v3
	v_lshrrev_b32_e32 v1, 26, v1
	v_ashrrev_i32_e32 v17, 6, v3
	v_add_u32_e32 v1, v0, v1
	v_lshlrev_b32_e32 v3, 3, v17
	v_ashrrev_i32_e32 v16, 6, v1
	v_and_b32_e32 v3, -16, v3
	v_add_u32_e32 v3, v16, v3
	v_and_b32_e32 v4, 3, v16
	s_add_u32 s36, s90, 0xc00000
	v_and_or_b32 v4, v3, s4, v4
	v_readlane_b32 s4, v241, 38
	s_addc_u32 s37, s91, 0
	s_lshr_b32 s4, s4, 29
	s_add_i32 s4, s66, s4
	s_ashr_i32 s3, s2, 6
	s_ashr_i32 s1, s0, 31
	s_ashr_i32 s6, s4, 3
	s_and_b32 s4, s4, -8
	s_ashr_i32 s5, s2, 8
	s_lshl_b64 s[14:15], s[0:1], 8
	s_lshl_b32 s38, s3, 10
	s_sub_i32 s4, s66, s4
	s_cmp_lt_i32 s4, 0
	s_movk_i32 s39, 0x16c
	s_cselect_b32 s7, s39, 0x16b
	s_mul_i32 s4, s4, s7
	s_add_i32 s4, s4, s6
	s_mul_hi_i32 s6, s4, 0x2e8ba2e9
	s_lshr_b32 s7, s6, 31
	s_ashr_i32 s6, s6, 5
	v_lshrrev_b32_e32 v5, 2, v3
	v_lshlrev_b32_e32 v6, 1, v3
	v_and_b32_e32 v1, 0xc0, v1
	s_add_i32 s6, s6, s7
	v_and_b32_e32 v5, 4, v5
	v_and_b32_e32 v6, 24, v6
	v_sub_u32_e32 v0, v0, v1
	s_lshl_b32 s8, s6, 3
	v_or3_b32 v4, v4, v5, v6
	v_lshlrev_b32_e32 v5, 5, v17
	v_ashrrev_i16_sdwa v0, v2, sext(v0) dst_sel:DWORD dst_unused:UNUSED_PAD src0_sel:DWORD src1_sel:BYTE_0
	s_sub_i32 s7, 0x84, s8
	s_mulk_i32 s6, 0xb0
	v_and_b32_e32 v5, 32, v5
	v_bfe_i32 v18, v0, 0, 16
	s_min_u32 s9, s7, 8
	s_sub_i32 s10, s4, s6
	v_mul_lo_u32 v4, v4, s0
	v_add_u32_e32 v0, v5, v18
	v_lshlrev_b32_e32 v1, 11, v3
	s_sext_i32_i16 s4, s10
	v_cvt_f32_ubyte0_e32 v3, s9
	v_add_lshl_u32 v132, v4, v0, 1
	v_cvt_f32_i32_e32 v2, s4
	v_rcp_iflag_f32_e32 v4, v3
	v_lshl_add_u32 v134, v0, 1, v1
	s_ashr_i32 s4, s4, 30
	s_or_b32 s4, s4, 1
	v_mul_f32_e32 v0, v2, v4
	v_trunc_f32_e32 v0, v0
	v_fma_f32 v1, -v0, v3, v2
	v_cvt_i32_f32_e32 v0, v0
	v_cmp_ge_f32_e64 s[6:7], |v1|, v3
	s_and_b64 s[6:7], s[6:7], exec
	s_cselect_b32 s4, s4, 0
	v_readfirstlane_b32 s6, v0
	s_add_i32 s4, s6, s4
	s_mul_i32 s6, s4, s9
	s_sub_i32 s6, s10, s6
	s_sext_i32_i16 s6, s6
	s_add_i32 s8, s8, s6
	s_ashr_i32 s9, s8, 31
	s_bfe_i64 s[6:7], s[4:5], 0x100000
	s_lshl_b64 s[16:17], s[0:1], 9
	s_lshl_b64 s[12:13], s[8:9], 19
	s_mul_i32 s7, s16, s7
	s_mul_hi_u32 s9, s16, s6
	s_lshr_b64 s[10:11], s[0:1], 23
	s_add_i32 s7, s9, s7
	s_mul_i32 s9, s10, s6
	s_add_i32 s7, s7, s9
	s_mul_i32 s6, s16, s6
	s_add_u32 s10, s36, s6
	s_addc_u32 s11, s37, s7
	s_add_i32 s40, s38, 0
	s_add_i32 m0, s40, 0x10000
	v_mov_b32_e32 v133, 0
	global_load_lds_dwordx4 v132, s[10:11]
	s_add_i32 m0, s40, 0x12000
	s_add_u32 s6, s10, s14
	global_load_lds_dwordx4 v128, s[10:11]
	s_addc_u32 s7, s11, s15
	s_add_i32 m0, s40, 0x14000
	v_mov_b32_e32 v129, v133
	global_load_lds_dwordx4 v132, s[6:7]
	s_add_i32 m0, s40, 0x16000
	s_add_u32 s12, s86, s12
	s_addc_u32 s13, s87, s13
	s_add_i32 s41, s40, 0x2000
	global_load_lds_dwordx4 v128, s[6:7]
	s_mov_b32 m0, s40
	s_add_u32 s18, s12, 0x40000
	global_load_lds_dwordx4 v134, s[12:13]
	s_mov_b32 m0, s41
	s_addc_u32 s19, s13, 0
	s_add_i32 s42, s40, 0x4000
	global_load_lds_dwordx4 v130, s[12:13]
	s_mov_b32 m0, s42
	s_add_i32 s43, s40, 0x6000
	global_load_lds_dwordx4 v134, s[18:19]
	s_mov_b32 m0, s43
	v_mov_b32_e32 v135, v133
	global_load_lds_dwordx4 v130, s[18:19]
	v_mov_b32_e32 v131, v133
	s_cmp_eq_u32 s5, 1
	s_mov_b32 s44, 0
	v_lshl_add_u64 v[8:9], s[10:11], 0, v[132:133]
	v_lshl_add_u64 v[4:5], s[10:11], 0, v[128:129]
	v_lshl_add_u64 v[2:3], s[6:7], 0, v[132:133]
	v_lshl_add_u64 v[0:1], s[6:7], 0, v[128:129]
	v_lshl_add_u64 v[6:7], s[12:13], 0, v[134:135]
	s_cselect_b64 s[18:19], -1, 0
	s_cmp_lg_u32 s5, 1
	v_lshl_add_u64 v[10:11], s[12:13], 0, v[130:131]
	s_cbranch_scc1 .LBB0_938
	s_barrier

.LBB0_1014:
	s_or_b64 exec, exec, s[0:1]
	s_cmpk_lt_i32 s66, 0x200
	s_cselect_b64 s[0:1], -1, 0
	s_cmpk_gt_i32 s66, 0x1ff
	s_mov_b32 s42, 0
	s_waitcnt lgkmcnt(0)
	s_barrier
	s_nop 0
	s_cbranch_scc1 .LBB0_1016
	s_sub_i32 s2, s92, s66
	s_add_i32 s3, s2, 0x1ff
	s_sub_i32 s2, 0xfffffe01, s2
	s_max_i32 s2, s3, s2
	s_ashr_i32 s4, s3, 31
	v_readlane_b32 s5, v241, 37
	s_mul_hi_u32 s3, s2, s76
	s_xor_b32 s4, s4, s5
	s_mul_i32 s5, s3, s69
	s_sub_i32 s2, s2, s5
	s_add_i32 s5, s3, 1
	s_sub_i32 s6, s2, s69
	s_cmp_ge_u32 s2, s69
	s_cselect_b32 s3, s5, s3
	s_cselect_b32 s2, s6, s2
	s_add_i32 s5, s3, 1
	s_cmp_ge_u32 s2, s69
	s_cselect_b32 s2, s5, s3
	s_xor_b32 s2, s2, s4
	s_sub_i32 s42, s2, s4

; __device__ __forceinline__ bool static_tile(int i, int nM, int nN, int G, int c, int& pm, int& pn) {
;     const int nwg = nM * nN; const long Lx = (long)i * G + c; if (Lx >= nwg) return false;
;     int wgid = (int)Lx; { const int q = nwg / NXCD, r = nwg % NXCD, xcd = wgid % NXCD, off = wgid / NXCD; wgid = (xcd < r ? xcd * (q + 1) : r * (q + 1) + (xcd - r) * q) + off; }
;     const int nig = WGM * nN, gid = wgid / nig, fm = gid * WGM, gsz = (nM - fm) < WGM ? (nM - fm) : WGM;
;     pm = fm + ((wgid % nig) % gsz); pn = (wgid % nig) / gsz; return true;
.LBB0_1500:
	s_or_b64 exec, exec, s[0:1]
	s_waitcnt vmcnt(0) lgkmcnt(0)
	v_mov_b32_e32 v0, v181
	s_barrier
	s_nop 0
	s_nop 0
	s_nop 0
	s_nop 0
	s_nop 0
	s_nop 0
	s_nop 0
	s_nop 0
	s_nop 0
	s_nop 0
	s_movk_i32 s0, 0x100
	v_readfirstlane_b32 s2, v0
	s_and_b64 vcc, exec, s[78:79]
	s_cbranch_vccnz .LBB0_1502
	v_readlane_b32 s1, v241, 38
	s_lshr_b32 s1, s1, 29
	s_add_i32 s1, s64, s1
	s_ashr_i32 s3, s1, 3
	s_and_b32 s1, s1, -8
	s_sub_i32 s1, s64, s1
	s_cmp_lt_i32 s1, 0
	s_movk_i32 s6, 0x43
	s_cselect_b32 s6, s6, 0x42
	s_mul_i32 s1, s1, s6
	s_add_i32 s1, s1, s3
	s_ashr_i32 s3, s1, 31
	s_lshr_b32 s3, s3, 27
	s_add_i32 s3, s1, s3
	s_ashr_i32 s3, s3, 5
	s_lshl_b32 s8, s3, 3
	s_sub_i32 s6, 0x84, s8
	s_lshl_b32 s3, s3, 5
	s_min_u32 s9, s6, 8
	s_sub_i32 s1, s1, s3
	s_sext_i32_i8 s3, s1
	v_cvt_f32_ubyte0_e32 v2, s9
	v_cvt_f32_i32_e32 v1, s3
	v_rcp_iflag_f32_e32 v3, v2
	s_ashr_i32 s3, s3, 30
	s_or_b32 s3, s3, 1
	v_mul_f32_e32 v3, v1, v3
	v_trunc_f32_e32 v3, v3
	v_fma_f32 v1, -v3, v2, v1
	v_cvt_i32_f32_e32 v3, v3
	v_cmp_ge_f32_e64 s[6:7], |v1|, v2
	s_and_b64 s[6:7], s[6:7], exec
	s_cselect_b32 s3, s3, 0
	v_readfirstlane_b32 s6, v3
	s_add_i32 s3, s6, s3
	s_sext_i32_i8 s38, s3
	s_mul_i32 s3, s3, s9
	s_sub_i32 s1, s1, s3
	s_sext_i32_i8 s1, s1
	s_add_i32 s40, s8, s1

;     __device__ __forceinline__ bool next(int i, Unit& u) const { u.kb = 0; u.nk = 0; return static_tile(i, nM, nN, G, c, u.pm, u.pn); }
; #define PG8_STAGE(bufoff, gbase, voff) do { _Pragma("unroll") for (int _i = 0; _i < 2; ++_i) \
;         __builtin_amdgcn_global_load_lds((const unsigned*)((const char*)(gbase) + (voff)[_i]), (PG8_LAS unsigned*)(lds + (bufoff) + ldsw + _i * 8192), 16, 0, 0); } while (0)
; #define PG8_WAIT_V(n) asm volatile("s_waitcnt vmcnt(" #n ")" ::: "memory")
; #define PG8_BAR __builtin_amdgcn_s_barrier()
; __device__ __forceinline__ bool static_tile(int i, int nM, int nN, int G, int c, int& pm, int& pn) {
;     const int nwg = nM * nN; const long Lx = (long)i * G + c; if (Lx >= nwg) return false;
;     int wgid = (int)Lx; { const int q = nwg / NXCD, r = nwg % NXCD, xcd = wgid % NXCD, off = wgid / NXCD; wgid = (xcd < r ? xcd * (q + 1) : r * (q + 1) + (xcd - r) * q) + off; }
;     const int nig = WGM * nN, gid = wgid / nig, fm = gid * WGM, gsz = (nM - fm) < WGM ? (nM - fm) : WGM;
;     pm = fm + ((wgid % nig) % gsz); pn = (wgid % nig) / gsz; return true;
; template <class Epi, class Sched>
; __device__ __forceinline__ void gemm_phase(PG8_LAS unsigned char* lds, const Gemm g, const Sched& S, const Epi& E) {
;     ...
;     for (int i = 0; i < 2; ++i) { int R, C; stage_rc(tid * 16 + i * 8192, R, C); const int Rb = (R & ~31) + perm32(R & 31);
;         voffA[i] = (unsigned)(R * g.lda + C) * 2u; voffB[i] = (unsigned)(Rb * K + C) * 2u; }
;     const size_t kstep = (size_t)(BK * 2);
;     const size_t hstepA = (size_t)HALF * g.lda * 2, hstepB = (size_t)HALF * K * 2;
;     const unsigned ldsw = (unsigned)wid * 1024u;
;     const int aoff = lds_byte(wr * 64 + fr, fq * 8), boff = lds_byte(wc * 32 + fr, fq * 8);
;     ...
;     Unit cur, nxt; int ui = 0;
;     if (!S.next(0, cur)) return;
;     f32x4 acc[2][2][4][2];
;     E.init(acc, cur, wr, wc, fr, fq);
;     bf16x8 At[4][2], B0[2][2], B1[2][2];
;     const char* cA = PG8_TA(cur); const char* cB = PG8_TB(cur);
;     PG8_STAGE(PG8_SB(0, 0), cB, voffB); PG8_STAGE(PG8_SB(0, 1), cB + hstepB, voffB); PG8_STAGE(PG8_SA(0, 0), cA, voffA); PG8_STAGE(PG8_SA(0, 1), cA + hstepA, voffA);
;     if (wr == 1) PG8_BAR;
;     PG8_WAIT_V(2); PG8_BAR;
;     PG8_STAGE(PG8_SB(1, 0), cB + kstep, voffB); PG8_STAGE(PG8_SA(1, 0), cA + kstep, voffA); PG8_STAGE(PG8_SB(1, 1), cB + hstepB + kstep, voffB);
.LBB0_1589:
	s_or_b64 exec, exec, s[0:1]
	v_mov_b32_e32 v13, v181
	s_waitcnt lgkmcnt(0)
	s_barrier
	s_nop 0
	s_nop 0
	s_nop 0
	s_nop 0
	s_nop 0
	s_nop 0
	s_nop 0
	s_nop 0
	s_nop 0
	s_nop 0
	s_nop 0
	s_nop 0
	s_nop 0
	s_movk_i32 s0, 0x400
	v_readfirstlane_b32 s3, v13
	s_andn2_b64 vcc, exec, s[24:25]
	s_cbranch_vccnz .LBB0_1608
	v_lshlrev_b32_e32 v0, 4, v13
	v_add_u32_e32 v1, 0x2000, v0
	v_ashrrev_i32_e32 v2, 31, v1
	v_lshrrev_b32_e32 v2, 22, v2
	v_add_u32_e32 v2, v1, v2
	v_ashrrev_i32_e32 v12, 10, v2
	v_mul_i32_i24_e32 v2, 0x400, v12
	v_sub_u32_e32 v1, v1, v2
	v_lshrrev_b32_e32 v2, 4, v1
	v_bitop3_b32 v1, v2, v1, 32 bitop3:0x6c
	v_ashrrev_i32_e32 v2, 31, v1
	v_lshrrev_b32_e32 v2, 26, v2
	v_add_u32_e32 v2, v1, v2
	v_lshlrev_b32_e32 v3, 3, v12
	v_ashrrev_i32_e32 v14, 6, v2
	v_and_b32_e32 v3, -16, v3
	v_add_u32_e32 v3, v14, v3
	v_and_b32_e32 v4, 3, v14
	s_mov_b32 s2, 0x7fffffe0
	v_lshrrev_b32_e32 v5, 2, v3
	v_lshlrev_b32_e32 v6, 1, v3
	v_and_b32_e32 v2, 0xc0, v2
	v_and_or_b32 v4, v3, s2, v4
	v_and_b32_e32 v5, 4, v5
	v_and_b32_e32 v6, 24, v6
	v_sub_u32_e32 v1, v1, v2
	v_mov_b32_e32 v2, 1
	v_or3_b32 v4, v4, v5, v6
	v_lshlrev_b32_e32 v5, 5, v12
	v_ashrrev_i16_sdwa v1, v2, sext(v1) dst_sel:DWORD dst_unused:UNUSED_PAD src0_sel:DWORD src1_sel:BYTE_0
	v_and_b32_e32 v5, 32, v5
	v_bfe_i32 v15, v1, 0, 16
	v_mul_lo_u32 v4, v4, s0
	v_add_u32_e32 v1, v5, v15
	v_lshlrev_b32_e32 v3, 11, v3
	v_add_lshl_u32 v128, v4, v1, 1
	v_lshl_add_u32 v132, v1, 1, v3
	v_bfe_i32 v1, v13, 27, 1
	v_lshrrev_b32_e32 v1, 22, v1
	v_add_u32_e32 v1, v0, v1
	v_and_b32_e32 v1, 0xfffffc00, v1
	v_sub_u32_e32 v0, v0, v1
	v_lshrrev_b32_e32 v1, 4, v0
	v_ashrrev_i32_e32 v3, 31, v13
	v_bitop3_b32 v0, v1, v0, 32 bitop3:0x6c
	v_lshrrev_b32_e32 v3, 26, v3
	v_ashrrev_i32_e32 v1, 31, v0
	v_add_u32_e32 v3, v13, v3
	v_lshrrev_b32_e32 v1, 26, v1
	v_ashrrev_i32_e32 v17, 6, v3
	v_add_u32_e32 v1, v0, v1
	v_lshlrev_b32_e32 v3, 3, v17
	v_ashrrev_i32_e32 v16, 6, v1
	v_and_b32_e32 v3, -16, v3
	v_add_u32_e32 v3, v16, v3
	v_and_b32_e32 v4, 3, v16
	s_add_u32 s36, s90, 0x1700000
	v_and_or_b32 v4, v3, s2, v4
	v_readlane_b32 s2, v241, 38
	s_addc_u32 s37, s91, 0
	s_lshr_b32 s2, s2, 29
	s_add_i32 s2, s64, s2
	s_ashr_i32 s6, s3, 6
	s_ashr_i32 s1, s0, 31
	s_ashr_i32 s8, s2, 3
	s_and_b32 s2, s2, -8
	s_ashr_i32 s7, s3, 8
	s_lshl_b64 s[16:17], s[0:1], 8
	s_lshl_b32 s38, s6, 10
	s_sub_i32 s2, s64, s2
	s_cmp_lt_i32 s2, 0
	s_movk_i32 s39, 0x16c
	s_cselect_b32 s9, s39, 0x16b
	s_mul_i32 s2, s2, s9
	s_add_i32 s2, s2, s8
	s_mul_hi_i32 s8, s2, 0x2e8ba2e9
	s_lshr_b32 s9, s8, 31
	s_ashr_i32 s8, s8, 5
	v_lshrrev_b32_e32 v5, 2, v3
	v_lshlrev_b32_e32 v6, 1, v3
	v_and_b32_e32 v1, 0xc0, v1
	s_add_i32 s8, s8, s9
	v_and_b32_e32 v5, 4, v5
	v_and_b32_e32 v6, 24, v6
	v_sub_u32_e32 v0, v0, v1
	s_lshl_b32 s10, s8, 3
	v_or3_b32 v4, v4, v5, v6
	v_lshlrev_b32_e32 v5, 5, v17
	v_ashrrev_i16_sdwa v0, v2, sext(v0) dst_sel:DWORD dst_unused:UNUSED_PAD src0_sel:DWORD src1_sel:BYTE_0
	s_sub_i32 s9, 0x84, s10
	s_mulk_i32 s8, 0xb0
	v_and_b32_e32 v5, 32, v5
	v_bfe_i32 v18, v0, 0, 16
	s_min_u32 s11, s9, 8
	s_sub_i32 s12, s2, s8
	v_mul_lo_u32 v4, v4, s0
	v_add_u32_e32 v0, v5, v18
	v_lshlrev_b32_e32 v1, 11, v3
	s_sext_i32_i16 s2, s12
	v_cvt_f32_ubyte0_e32 v3, s11
	v_add_lshl_u32 v134, v4, v0, 1
	v_cvt_f32_i32_e32 v2, s2
	v_rcp_iflag_f32_e32 v4, v3
	v_lshl_add_u32 v136, v0, 1, v1
	s_ashr_i32 s2, s2, 30
	s_or_b32 s2, s2, 1
	v_mul_f32_e32 v0, v2, v4
	v_trunc_f32_e32 v0, v0
	v_fma_f32 v1, -v0, v3, v2
	v_cvt_i32_f32_e32 v0, v0
	v_cmp_ge_f32_e64 s[8:9], |v1|, v3
	s_and_b64 s[8:9], s[8:9], exec
	s_cselect_b32 s2, s2, 0
	v_readfirstlane_b32 s8, v0
	s_add_i32 s2, s8, s2
	s_mul_i32 s8, s2, s11
	s_sub_i32 s8, s12, s8
	s_sext_i32_i16 s8, s8
	s_add_i32 s8, s10, s8
	s_ashr_i32 s9, s8, 31
	s_bfe_i64 s[10:11], s[2:3], 0x100000
	s_lshl_b64 s[18:19], s[0:1], 9
	s_lshl_b64 s[12:13], s[8:9], 19
	s_mul_i32 s9, s18, s11
	s_mul_hi_u32 s11, s18, s10
	s_lshr_b64 s[20:21], s[0:1], 23
	s_add_i32 s9, s11, s9
	s_mul_i32 s11, s20, s10
	s_add_i32 s9, s9, s11
	s_mul_i32 s10, s18, s10
	s_add_u32 s10, s36, s10
	s_addc_u32 s11, s37, s9
	s_add_i32 s40, s38, 0
	s_add_i32 m0, s40, 0x10000
	v_mov_b32_e32 v135, 0
	global_load_lds_dwordx4 v134, s[10:11]
	s_add_i32 m0, s40, 0x12000
	s_add_u32 s20, s10, s16
	global_load_lds_dwordx4 v128, s[10:11]
	s_addc_u32 s21, s11, s17
	s_add_i32 m0, s40, 0x14000
	v_mov_b32_e32 v129, v135
	global_load_lds_dwordx4 v134, s[20:21]
	s_add_i32 m0, s40, 0x16000
	s_add_u32 s12, s86, s12
	s_addc_u32 s13, s87, s13
	s_add_i32 s41, s40, 0x2000
	global_load_lds_dwordx4 v128, s[20:21]
	s_mov_b32 m0, s40
	s_add_u32 s24, s12, 0x40000
	global_load_lds_dwordx4 v136, s[12:13]
	s_mov_b32 m0, s41
	s_addc_u32 s25, s13, 0
	s_add_i32 s42, s40, 0x4000
	global_load_lds_dwordx4 v132, s[12:13]
	s_mov_b32 m0, s42
	s_add_i32 s43, s40, 0x6000
	global_load_lds_dwordx4 v136, s[24:25]
	s_mov_b32 m0, s43
	v_mov_b32_e32 v137, v135
	global_load_lds_dwordx4 v132, s[24:25]
	v_mov_b32_e32 v133, v135
	s_cmp_eq_u32 s7, 1
	s_mov_b32 s44, 0
	v_lshl_add_u64 v[8:9], s[10:11], 0, v[134:135]
	v_lshl_add_u64 v[4:5], s[10:11], 0, v[128:129]
	v_lshl_add_u64 v[2:3], s[20:21], 0, v[134:135]
	v_lshl_add_u64 v[0:1], s[20:21], 0, v[128:129]
	v_lshl_add_u64 v[6:7], s[12:13], 0, v[136:137]
	s_cselect_b64 s[20:21], -1, 0
	s_cmp_lg_u32 s7, 1
	v_lshl_add_u64 v[10:11], s[12:13], 0, v[132:133]
	s_cbranch_scc1 .LBB0_1592
	s_barrier

.LBB0_1660:
	s_or_b64 exec, exec, s[0:1]
	s_and_b64 vcc, exec, s[4:5]
	s_mov_b32 s34, 0
	s_waitcnt lgkmcnt(0)
	s_barrier
	s_nop 0
	s_cbranch_vccnz .LBB0_1662
	s_sub_i32 s0, s92, s64
	s_add_i32 s1, s0, 0x1ff
	s_sub_i32 s0, 0xfffffe01, s0
	s_max_i32 s0, s1, s0
	s_ashr_i32 s2, s1, 31
	v_readlane_b32 s3, v241, 37
	s_mul_hi_u32 s1, s0, s76
	s_xor_b32 s2, s2, s3
	s_mul_i32 s3, s1, s69
	s_sub_i32 s0, s0, s3
	s_add_i32 s3, s1, 1
	s_sub_i32 s6, s0, s69
	s_cmp_ge_u32 s0, s69
	s_cselect_b32 s1, s3, s1
	s_cselect_b32 s0, s6, s0
	s_add_i32 s3, s1, 1
	s_cmp_ge_u32 s0, s69
	s_cselect_b32 s0, s3, s1
	s_xor_b32 s0, s0, s2
	s_sub_i32 s34, s0, s2
